# gate unit: hoisted all per-iteration global loads to loop top with counted vmcnt waits; stats loop 16 loads in flight
# speedup vs baseline: 1.0063x; 1.0054x over previous
; __device__ __forceinline__ float bf_lo(unsigned w) { return __uint_as_float(w << 16); }
; __device__ __forceinline__ float bf_hi(unsigned w) { return __uint_as_float(w & 0xffff0000u); }
; __device__ __forceinline__ float shx(float v, int o, int lane) { return __int_as_float(__builtin_amdgcn_ds_bpermute((lane ^ o) << 2, __float_as_int(v))); }
; __device__ __forceinline__ void gate_unit(LAS unsigned char* lds, bf16_t* Zg, int ch, const bf16_t* wsb, const float* ln_g, const float* ln_b, const float* b_s, bool dostore = true) {
;     ...
;     {
;         const int row = tid >> 2, part = tid & 3; const bf16_t* src = Zc + (size_t)row * ZLD + COL_VB + part * 8;
;         float s = 0.f, s2 = 0.f;
; #pragma unroll 8
;         for (int i = 0; i < 32; ++i) { const u32x4 w = *(const u32x4*)(src + i * 32);
; #pragma unroll
;             for (int e = 0; e < 4; ++e) { const float a = bf_lo(w[e]), b = bf_hi(w[e]); s += a + b; s2 += a * a + b * b; } }
;         s += shx(s, 1, lane); s += shx(s, 2, lane); s2 += shx(s2, 1, lane); s2 += shx(s2, 2, lane);
;         const float mean = s * (1.0f / 1024.0f); const float var = fmaxf(s2 * (1.0f / 1024.0f) - mean * mean, 0.f);
;         if (part == 0) { stats[row * 2] = mean; stats[row * 2 + 1] = 1.0f / sqrtf(var + EPS); }
;     }
.LBB0_179:
	v_lshl_add_u64 v[14:15], v[2:3], 0, s[4:5]
	global_load_dwordx4 v[80:83], v[14:15], off offset:-256
	global_load_dwordx4 v[84:87], v[14:15], off offset:-192
	global_load_dwordx4 v[88:91], v[14:15], off offset:-128
	global_load_dwordx4 v[92:95], v[14:15], off offset:-64
	global_load_dwordx4 v[96:99], v[14:15], off
	global_load_dwordx4 v[100:103], v[14:15], off offset:64
	global_load_dwordx4 v[104:107], v[14:15], off offset:128
	global_load_dwordx4 v[108:111], v[14:15], off offset:192
	global_load_dwordx4 v[112:115], v[14:15], off offset:256
	global_load_dwordx4 v[116:119], v[14:15], off offset:320
	global_load_dwordx4 v[120:123], v[14:15], off offset:384
	global_load_dwordx4 v[124:127], v[14:15], off offset:448
	global_load_dwordx4 v[128:131], v[14:15], off offset:512
	global_load_dwordx4 v[132:135], v[14:15], off offset:576
	global_load_dwordx4 v[136:139], v[14:15], off offset:640
	global_load_dwordx4 v[140:143], v[14:15], off offset:704
	s_add_u32 s4, s4, 0x400
	s_addc_u32 s5, s5, 0
	s_cmpk_eq_i32 s4, 0x800
	s_waitcnt vmcnt(15)
	v_lshlrev_b32_e32 v17, 16, v81
	v_lshlrev_b32_e32 v16, 16, v80
	v_and_b32_e32 v81, 0xffff0000, v81
	v_and_b32_e32 v80, 0xffff0000, v80
	v_pk_add_f32 v[18:19], v[16:17], v[80:81]
	v_pk_mul_f32 v[80:81], v[80:81], v[80:81]
	v_pk_add_f32 v[20:21], v[4:5], v[18:19]
	v_pk_fma_f32 v[80:81], v[16:17], v[16:17], v[80:81]
	s_nop 0
	v_add_f32_e32 v0, v5, v80
	v_pk_add_f32 v[4:5], v[80:81], v[0:1] op_sel_hi:[1,0]
	v_and_b32_e32 v80, 0xffff0000, v82
	v_lshlrev_b32_e32 v82, 16, v82
	v_and_b32_e32 v4, 0xffff0000, v83
	v_lshlrev_b32_e32 v83, 16, v83
	v_mov_b32_e32 v16, v82
	v_mov_b32_e32 v17, v80
	v_mul_f32_e32 v0, v82, v82
	v_mov_b32_e32 v81, v83
	v_pk_fma_f32 v[16:17], v[16:17], v[16:17], v[0:1] op_sel_hi:[1,1,0]
	v_pk_add_f32 v[80:81], v[82:83], v[80:81]
	v_mov_b32_e32 v16, v83
	v_pk_mul_f32 v[82:83], v[82:83], v[82:83]
	v_mul_f32_e32 v9, v4, v4
	v_mov_b32_e32 v81, v83
	v_pk_add_f32 v[82:83], v[18:19], v[20:21] op_sel:[1,0] op_sel_hi:[0,1]
	v_mov_b32_e32 v83, v9
	v_pk_add_f32 v[4:5], v[16:17], v[4:5]
	v_pk_add_f32 v[80:81], v[80:81], v[82:83]
	s_nop 0
	v_pk_add_f32 v[4:5], v[80:81], v[4:5]
	s_waitcnt vmcnt(14)
	v_lshlrev_b32_e32 v17, 16, v85
	v_lshlrev_b32_e32 v16, 16, v84
	v_and_b32_e32 v85, 0xffff0000, v85
	v_and_b32_e32 v84, 0xffff0000, v84
	v_pk_add_f32 v[18:19], v[16:17], v[84:85]
	v_pk_mul_f32 v[84:85], v[84:85], v[84:85]
	v_pk_add_f32 v[20:21], v[4:5], v[18:19]
	v_pk_fma_f32 v[84:85], v[16:17], v[16:17], v[84:85]
	s_nop 0
	v_add_f32_e32 v0, v5, v84
	v_pk_add_f32 v[4:5], v[84:85], v[0:1] op_sel_hi:[1,0]
	v_and_b32_e32 v84, 0xffff0000, v86
	v_lshlrev_b32_e32 v86, 16, v86
	v_and_b32_e32 v4, 0xffff0000, v87
	v_lshlrev_b32_e32 v87, 16, v87
	v_mov_b32_e32 v16, v86
	v_mov_b32_e32 v17, v84
	v_mul_f32_e32 v0, v86, v86
	v_mov_b32_e32 v85, v87
	v_pk_fma_f32 v[16:17], v[16:17], v[16:17], v[0:1] op_sel_hi:[1,1,0]
	v_pk_add_f32 v[84:85], v[86:87], v[84:85]
	v_mov_b32_e32 v16, v87
	v_pk_mul_f32 v[86:87], v[86:87], v[86:87]
	v_mul_f32_e32 v9, v4, v4
	v_mov_b32_e32 v85, v87
	v_pk_add_f32 v[86:87], v[18:19], v[20:21] op_sel:[1,0] op_sel_hi:[0,1]
	v_mov_b32_e32 v87, v9
	v_pk_add_f32 v[4:5], v[16:17], v[4:5]
	v_pk_add_f32 v[84:85], v[84:85], v[86:87]
	s_nop 0
	v_pk_add_f32 v[4:5], v[84:85], v[4:5]
	s_waitcnt vmcnt(13)
	v_lshlrev_b32_e32 v17, 16, v89
	v_lshlrev_b32_e32 v16, 16, v88
	v_and_b32_e32 v89, 0xffff0000, v89
	v_and_b32_e32 v88, 0xffff0000, v88
	v_pk_add_f32 v[18:19], v[16:17], v[88:89]
	v_pk_mul_f32 v[88:89], v[88:89], v[88:89]
	v_pk_add_f32 v[20:21], v[4:5], v[18:19]
	v_pk_fma_f32 v[88:89], v[16:17], v[16:17], v[88:89]
	s_nop 0
	v_add_f32_e32 v0, v5, v88
	v_pk_add_f32 v[4:5], v[88:89], v[0:1] op_sel_hi:[1,0]
	v_and_b32_e32 v88, 0xffff0000, v90
	v_lshlrev_b32_e32 v90, 16, v90
	v_and_b32_e32 v4, 0xffff0000, v91
	v_lshlrev_b32_e32 v91, 16, v91
	v_mov_b32_e32 v16, v90
	v_mov_b32_e32 v17, v88
	v_mul_f32_e32 v0, v90, v90
	v_mov_b32_e32 v89, v91
	v_pk_fma_f32 v[16:17], v[16:17], v[16:17], v[0:1] op_sel_hi:[1,1,0]
	v_pk_add_f32 v[88:89], v[90:91], v[88:89]
	v_mov_b32_e32 v16, v91
	v_pk_mul_f32 v[90:91], v[90:91], v[90:91]
	v_mul_f32_e32 v9, v4, v4
	v_mov_b32_e32 v89, v91
	v_pk_add_f32 v[90:91], v[18:19], v[20:21] op_sel:[1,0] op_sel_hi:[0,1]
	v_mov_b32_e32 v91, v9
	v_pk_add_f32 v[4:5], v[16:17], v[4:5]
	v_pk_add_f32 v[88:89], v[88:89], v[90:91]
	s_nop 0
	v_pk_add_f32 v[4:5], v[88:89], v[4:5]
	s_waitcnt vmcnt(12)
	v_lshlrev_b32_e32 v17, 16, v93
	v_lshlrev_b32_e32 v16, 16, v92
	v_and_b32_e32 v93, 0xffff0000, v93
	v_and_b32_e32 v92, 0xffff0000, v92
	v_pk_add_f32 v[18:19], v[16:17], v[92:93]
	v_pk_mul_f32 v[92:93], v[92:93], v[92:93]
	v_pk_add_f32 v[20:21], v[4:5], v[18:19]
	v_pk_fma_f32 v[92:93], v[16:17], v[16:17], v[92:93]
	s_nop 0
	v_add_f32_e32 v0, v5, v92
	v_pk_add_f32 v[4:5], v[92:93], v[0:1] op_sel_hi:[1,0]
	v_and_b32_e32 v92, 0xffff0000, v94
	v_lshlrev_b32_e32 v94, 16, v94
	v_and_b32_e32 v4, 0xffff0000, v95
	v_lshlrev_b32_e32 v95, 16, v95
	v_mov_b32_e32 v16, v94
	v_mov_b32_e32 v17, v92
	v_mul_f32_e32 v0, v94, v94
	v_mov_b32_e32 v93, v95
	v_pk_fma_f32 v[16:17], v[16:17], v[16:17], v[0:1] op_sel_hi:[1,1,0]
	v_pk_add_f32 v[92:93], v[94:95], v[92:93]
	v_mov_b32_e32 v16, v95
	v_pk_mul_f32 v[94:95], v[94:95], v[94:95]
	v_mul_f32_e32 v9, v4, v4
	v_mov_b32_e32 v93, v95
	v_pk_add_f32 v[94:95], v[18:19], v[20:21] op_sel:[1,0] op_sel_hi:[0,1]
	v_mov_b32_e32 v95, v9
	v_pk_add_f32 v[4:5], v[16:17], v[4:5]
	v_pk_add_f32 v[92:93], v[92:93], v[94:95]
	s_nop 0
	v_pk_add_f32 v[4:5], v[92:93], v[4:5]
	s_waitcnt vmcnt(11)
; __device__ __forceinline__ float bf_lo(unsigned w) { return __uint_as_float(w << 16); }
; __device__ __forceinline__ float bf_hi(unsigned w) { return __uint_as_float(w & 0xffff0000u); }
; __device__ __forceinline__ float shx(float v, int o, int lane) { return __int_as_float(__builtin_amdgcn_ds_bpermute((lane ^ o) << 2, __float_as_int(v))); }
; __device__ __forceinline__ void gate_unit(LAS unsigned char* lds, bf16_t* Zg, int ch, const bf16_t* wsb, const float* ln_g, const float* ln_b, const float* b_s, bool dostore = true) {
;     ...
;     {
;         const int row = tid >> 2, part = tid & 3; const bf16_t* src = Zc + (size_t)row * ZLD + COL_VB + part * 8;
;         float s = 0.f, s2 = 0.f;
; #pragma unroll 8
;         for (int i = 0; i < 32; ++i) { const u32x4 w = *(const u32x4*)(src + i * 32);
; #pragma unroll
;             for (int e = 0; e < 4; ++e) { const float a = bf_lo(w[e]), b = bf_hi(w[e]); s += a + b; s2 += a * a + b * b; } }
;         s += shx(s, 1, lane); s += shx(s, 2, lane); s2 += shx(s2, 1, lane); s2 += shx(s2, 2, lane);
;         const float mean = s * (1.0f / 1024.0f); const float var = fmaxf(s2 * (1.0f / 1024.0f) - mean * mean, 0.f);
;         if (part == 0) { stats[row * 2] = mean; stats[row * 2 + 1] = 1.0f / sqrtf(var + EPS); }
;     }
	v_lshlrev_b32_e32 v17, 16, v97
	v_lshlrev_b32_e32 v16, 16, v96
	v_and_b32_e32 v97, 0xffff0000, v97
	v_and_b32_e32 v96, 0xffff0000, v96
	v_pk_add_f32 v[18:19], v[16:17], v[96:97]
	v_pk_mul_f32 v[96:97], v[96:97], v[96:97]
	v_pk_add_f32 v[20:21], v[4:5], v[18:19]
	v_pk_fma_f32 v[96:97], v[16:17], v[16:17], v[96:97]
	s_nop 0
	v_add_f32_e32 v0, v5, v96
	v_pk_add_f32 v[4:5], v[96:97], v[0:1] op_sel_hi:[1,0]
	v_and_b32_e32 v96, 0xffff0000, v98
	v_lshlrev_b32_e32 v98, 16, v98
	v_and_b32_e32 v4, 0xffff0000, v99
	v_lshlrev_b32_e32 v99, 16, v99
	v_mov_b32_e32 v16, v98
	v_mov_b32_e32 v17, v96
	v_mul_f32_e32 v0, v98, v98
	v_mov_b32_e32 v97, v99
	v_pk_fma_f32 v[16:17], v[16:17], v[16:17], v[0:1] op_sel_hi:[1,1,0]
	v_pk_add_f32 v[96:97], v[98:99], v[96:97]
	v_mov_b32_e32 v16, v99
	v_pk_mul_f32 v[98:99], v[98:99], v[98:99]
	v_mul_f32_e32 v9, v4, v4
	v_mov_b32_e32 v97, v99
	v_pk_add_f32 v[98:99], v[18:19], v[20:21] op_sel:[1,0] op_sel_hi:[0,1]
	v_mov_b32_e32 v99, v9
	v_pk_add_f32 v[4:5], v[16:17], v[4:5]
	v_pk_add_f32 v[96:97], v[96:97], v[98:99]
	s_nop 0
	v_pk_add_f32 v[4:5], v[96:97], v[4:5]
	s_waitcnt vmcnt(10)
	v_lshlrev_b32_e32 v17, 16, v101
	v_lshlrev_b32_e32 v16, 16, v100
	v_and_b32_e32 v101, 0xffff0000, v101
	v_and_b32_e32 v100, 0xffff0000, v100
	v_pk_add_f32 v[18:19], v[16:17], v[100:101]
	v_pk_mul_f32 v[100:101], v[100:101], v[100:101]
	v_pk_add_f32 v[20:21], v[4:5], v[18:19]
	v_pk_fma_f32 v[100:101], v[16:17], v[16:17], v[100:101]
	s_nop 0
	v_add_f32_e32 v0, v5, v100
	v_pk_add_f32 v[4:5], v[100:101], v[0:1] op_sel_hi:[1,0]
	v_and_b32_e32 v100, 0xffff0000, v102
	v_lshlrev_b32_e32 v102, 16, v102
	v_and_b32_e32 v4, 0xffff0000, v103
	v_lshlrev_b32_e32 v103, 16, v103
	v_mov_b32_e32 v16, v102
	v_mov_b32_e32 v17, v100
	v_mul_f32_e32 v0, v102, v102
	v_mov_b32_e32 v101, v103
	v_pk_fma_f32 v[16:17], v[16:17], v[16:17], v[0:1] op_sel_hi:[1,1,0]
	v_pk_add_f32 v[100:101], v[102:103], v[100:101]
	v_mov_b32_e32 v16, v103
	v_pk_mul_f32 v[102:103], v[102:103], v[102:103]
	v_mul_f32_e32 v9, v4, v4
	v_mov_b32_e32 v101, v103
	v_pk_add_f32 v[102:103], v[18:19], v[20:21] op_sel:[1,0] op_sel_hi:[0,1]
	v_mov_b32_e32 v103, v9
	v_pk_add_f32 v[4:5], v[16:17], v[4:5]
	v_pk_add_f32 v[100:101], v[100:101], v[102:103]
	s_nop 0
	v_pk_add_f32 v[4:5], v[100:101], v[4:5]
	s_waitcnt vmcnt(9)
	v_lshlrev_b32_e32 v17, 16, v105
	v_lshlrev_b32_e32 v16, 16, v104
	v_and_b32_e32 v105, 0xffff0000, v105
	v_and_b32_e32 v104, 0xffff0000, v104
	v_pk_add_f32 v[18:19], v[16:17], v[104:105]
	v_pk_mul_f32 v[104:105], v[104:105], v[104:105]
	v_pk_add_f32 v[20:21], v[4:5], v[18:19]
	v_pk_fma_f32 v[104:105], v[16:17], v[16:17], v[104:105]
	s_nop 0
	v_add_f32_e32 v0, v5, v104
	v_pk_add_f32 v[4:5], v[104:105], v[0:1] op_sel_hi:[1,0]
	v_and_b32_e32 v104, 0xffff0000, v106
	v_lshlrev_b32_e32 v106, 16, v106
	v_and_b32_e32 v4, 0xffff0000, v107
	v_lshlrev_b32_e32 v107, 16, v107
	v_mov_b32_e32 v16, v106
	v_mov_b32_e32 v17, v104
	v_mul_f32_e32 v0, v106, v106
	v_mov_b32_e32 v105, v107
	v_pk_fma_f32 v[16:17], v[16:17], v[16:17], v[0:1] op_sel_hi:[1,1,0]
	v_pk_add_f32 v[104:105], v[106:107], v[104:105]
	v_mov_b32_e32 v16, v107
	v_pk_mul_f32 v[106:107], v[106:107], v[106:107]
	v_mul_f32_e32 v9, v4, v4
	v_mov_b32_e32 v105, v107
	v_pk_add_f32 v[106:107], v[18:19], v[20:21] op_sel:[1,0] op_sel_hi:[0,1]
	v_mov_b32_e32 v107, v9
	v_pk_add_f32 v[4:5], v[16:17], v[4:5]
	v_pk_add_f32 v[104:105], v[104:105], v[106:107]
	s_nop 0
	v_pk_add_f32 v[4:5], v[104:105], v[4:5]
	s_waitcnt vmcnt(8)
	v_lshlrev_b32_e32 v15, 16, v109
	v_lshlrev_b32_e32 v14, 16, v108
	v_and_b32_e32 v109, 0xffff0000, v109
	v_and_b32_e32 v108, 0xffff0000, v108
	v_pk_add_f32 v[16:17], v[14:15], v[108:109]
	v_pk_mul_f32 v[108:109], v[108:109], v[108:109]
	v_pk_add_f32 v[18:19], v[4:5], v[16:17]
	v_pk_fma_f32 v[108:109], v[14:15], v[14:15], v[108:109]
	s_nop 0
	v_add_f32_e32 v0, v5, v108
	v_pk_add_f32 v[4:5], v[108:109], v[0:1] op_sel_hi:[1,0]
	v_and_b32_e32 v108, 0xffff0000, v110
	v_lshlrev_b32_e32 v110, 16, v110
	v_and_b32_e32 v4, 0xffff0000, v111
	v_lshlrev_b32_e32 v111, 16, v111
	v_mov_b32_e32 v14, v110
	v_mov_b32_e32 v15, v108
	v_mul_f32_e32 v0, v110, v110
	v_mov_b32_e32 v109, v111
	v_pk_fma_f32 v[14:15], v[14:15], v[14:15], v[0:1] op_sel_hi:[1,1,0]
	v_pk_add_f32 v[108:109], v[110:111], v[108:109]
	v_mov_b32_e32 v14, v111
	v_pk_mul_f32 v[110:111], v[110:111], v[110:111]
	v_mul_f32_e32 v9, v4, v4
	v_mov_b32_e32 v109, v111
	v_pk_add_f32 v[110:111], v[16:17], v[18:19] op_sel:[1,0] op_sel_hi:[0,1]
	v_mov_b32_e32 v111, v9
	v_pk_add_f32 v[4:5], v[14:15], v[4:5]
	v_pk_add_f32 v[108:109], v[108:109], v[110:111]
	s_nop 0
	v_pk_add_f32 v[4:5], v[108:109], v[4:5]
	s_waitcnt vmcnt(7)
	v_lshlrev_b32_e32 v17, 16, v113
	v_lshlrev_b32_e32 v16, 16, v112
	v_and_b32_e32 v113, 0xffff0000, v113
	v_and_b32_e32 v112, 0xffff0000, v112
	v_pk_add_f32 v[18:19], v[16:17], v[112:113]
	v_pk_mul_f32 v[112:113], v[112:113], v[112:113]
	v_pk_add_f32 v[20:21], v[4:5], v[18:19]
	v_pk_fma_f32 v[112:113], v[16:17], v[16:17], v[112:113]
	s_nop 0
	v_add_f32_e32 v0, v5, v112
	v_pk_add_f32 v[4:5], v[112:113], v[0:1] op_sel_hi:[1,0]
	v_and_b32_e32 v112, 0xffff0000, v114
	v_lshlrev_b32_e32 v114, 16, v114
	v_and_b32_e32 v4, 0xffff0000, v115
	v_lshlrev_b32_e32 v115, 16, v115
	v_mov_b32_e32 v16, v114
	v_mov_b32_e32 v17, v112
	v_mul_f32_e32 v0, v114, v114
	v_mov_b32_e32 v113, v115
	v_pk_fma_f32 v[16:17], v[16:17], v[16:17], v[0:1] op_sel_hi:[1,1,0]
	v_pk_add_f32 v[112:113], v[114:115], v[112:113]
	v_mov_b32_e32 v16, v115
	v_pk_mul_f32 v[114:115], v[114:115], v[114:115]
	v_mul_f32_e32 v9, v4, v4
	v_mov_b32_e32 v113, v115
	v_pk_add_f32 v[114:115], v[18:19], v[20:21] op_sel:[1,0] op_sel_hi:[0,1]
	v_mov_b32_e32 v115, v9
	v_pk_add_f32 v[4:5], v[16:17], v[4:5]
	v_pk_add_f32 v[112:113], v[112:113], v[114:115]
	s_nop 0
	v_pk_add_f32 v[4:5], v[112:113], v[4:5]
	s_waitcnt vmcnt(6)
; __device__ __forceinline__ float bf_lo(unsigned w) { return __uint_as_float(w << 16); }
; __device__ __forceinline__ float bf_hi(unsigned w) { return __uint_as_float(w & 0xffff0000u); }
; __device__ __forceinline__ float shx(float v, int o, int lane) { return __int_as_float(__builtin_amdgcn_ds_bpermute((lane ^ o) << 2, __float_as_int(v))); }
; __device__ __forceinline__ void gate_unit(LAS unsigned char* lds, bf16_t* Zg, int ch, const bf16_t* wsb, const float* ln_g, const float* ln_b, const float* b_s, bool dostore = true) {
;     ...
;     {
;         const int row = tid >> 2, part = tid & 3; const bf16_t* src = Zc + (size_t)row * ZLD + COL_VB + part * 8;
;         float s = 0.f, s2 = 0.f;
; #pragma unroll 8
;         for (int i = 0; i < 32; ++i) { const u32x4 w = *(const u32x4*)(src + i * 32);
; #pragma unroll
;             for (int e = 0; e < 4; ++e) { const float a = bf_lo(w[e]), b = bf_hi(w[e]); s += a + b; s2 += a * a + b * b; } }
;         s += shx(s, 1, lane); s += shx(s, 2, lane); s2 += shx(s2, 1, lane); s2 += shx(s2, 2, lane);
;         const float mean = s * (1.0f / 1024.0f); const float var = fmaxf(s2 * (1.0f / 1024.0f) - mean * mean, 0.f);
;         if (part == 0) { stats[row * 2] = mean; stats[row * 2 + 1] = 1.0f / sqrtf(var + EPS); }
;     }
	v_lshlrev_b32_e32 v17, 16, v117
	v_lshlrev_b32_e32 v16, 16, v116
	v_and_b32_e32 v117, 0xffff0000, v117
	v_and_b32_e32 v116, 0xffff0000, v116
	v_pk_add_f32 v[18:19], v[16:17], v[116:117]
	v_pk_mul_f32 v[116:117], v[116:117], v[116:117]
	v_pk_add_f32 v[20:21], v[4:5], v[18:19]
	v_pk_fma_f32 v[116:117], v[16:17], v[16:17], v[116:117]
	s_nop 0
	v_add_f32_e32 v0, v5, v116
	v_pk_add_f32 v[4:5], v[116:117], v[0:1] op_sel_hi:[1,0]
	v_and_b32_e32 v116, 0xffff0000, v118
	v_lshlrev_b32_e32 v118, 16, v118
	v_and_b32_e32 v4, 0xffff0000, v119
	v_lshlrev_b32_e32 v119, 16, v119
	v_mov_b32_e32 v16, v118
	v_mov_b32_e32 v17, v116
	v_mul_f32_e32 v0, v118, v118
	v_mov_b32_e32 v117, v119
	v_pk_fma_f32 v[16:17], v[16:17], v[16:17], v[0:1] op_sel_hi:[1,1,0]
	v_pk_add_f32 v[116:117], v[118:119], v[116:117]
	v_mov_b32_e32 v16, v119
	v_pk_mul_f32 v[118:119], v[118:119], v[118:119]
	v_mul_f32_e32 v9, v4, v4
	v_mov_b32_e32 v117, v119
	v_pk_add_f32 v[118:119], v[18:19], v[20:21] op_sel:[1,0] op_sel_hi:[0,1]
	v_mov_b32_e32 v119, v9
	v_pk_add_f32 v[4:5], v[16:17], v[4:5]
	v_pk_add_f32 v[116:117], v[116:117], v[118:119]
	s_nop 0
	v_pk_add_f32 v[4:5], v[116:117], v[4:5]
	s_waitcnt vmcnt(5)
	v_lshlrev_b32_e32 v17, 16, v121
	v_lshlrev_b32_e32 v16, 16, v120
	v_and_b32_e32 v121, 0xffff0000, v121
	v_and_b32_e32 v120, 0xffff0000, v120
	v_pk_add_f32 v[18:19], v[16:17], v[120:121]
	v_pk_mul_f32 v[120:121], v[120:121], v[120:121]
	v_pk_add_f32 v[20:21], v[4:5], v[18:19]
	v_pk_fma_f32 v[120:121], v[16:17], v[16:17], v[120:121]
	s_nop 0
	v_add_f32_e32 v0, v5, v120
	v_pk_add_f32 v[4:5], v[120:121], v[0:1] op_sel_hi:[1,0]
	v_and_b32_e32 v120, 0xffff0000, v122
	v_lshlrev_b32_e32 v122, 16, v122
	v_and_b32_e32 v4, 0xffff0000, v123
	v_lshlrev_b32_e32 v123, 16, v123
	v_mov_b32_e32 v16, v122
	v_mov_b32_e32 v17, v120
	v_mul_f32_e32 v0, v122, v122
	v_mov_b32_e32 v121, v123
	v_pk_fma_f32 v[16:17], v[16:17], v[16:17], v[0:1] op_sel_hi:[1,1,0]
	v_pk_add_f32 v[120:121], v[122:123], v[120:121]
	v_mov_b32_e32 v16, v123
	v_pk_mul_f32 v[122:123], v[122:123], v[122:123]
	v_mul_f32_e32 v9, v4, v4
	v_mov_b32_e32 v121, v123
	v_pk_add_f32 v[122:123], v[18:19], v[20:21] op_sel:[1,0] op_sel_hi:[0,1]
	v_mov_b32_e32 v123, v9
	v_pk_add_f32 v[4:5], v[16:17], v[4:5]
	v_pk_add_f32 v[120:121], v[120:121], v[122:123]
	s_nop 0
	v_pk_add_f32 v[4:5], v[120:121], v[4:5]
	s_waitcnt vmcnt(4)
	v_lshlrev_b32_e32 v17, 16, v125
	v_lshlrev_b32_e32 v16, 16, v124
	v_and_b32_e32 v125, 0xffff0000, v125
	v_and_b32_e32 v124, 0xffff0000, v124
	v_pk_add_f32 v[18:19], v[16:17], v[124:125]
	v_pk_mul_f32 v[124:125], v[124:125], v[124:125]
	v_pk_add_f32 v[20:21], v[4:5], v[18:19]
	v_pk_fma_f32 v[124:125], v[16:17], v[16:17], v[124:125]
	s_nop 0
	v_add_f32_e32 v0, v5, v124
	v_pk_add_f32 v[4:5], v[124:125], v[0:1] op_sel_hi:[1,0]
	v_and_b32_e32 v124, 0xffff0000, v126
	v_lshlrev_b32_e32 v126, 16, v126
	v_and_b32_e32 v4, 0xffff0000, v127
	v_lshlrev_b32_e32 v127, 16, v127
	v_mov_b32_e32 v16, v126
	v_mov_b32_e32 v17, v124
	v_mul_f32_e32 v0, v126, v126
	v_mov_b32_e32 v125, v127
	v_pk_fma_f32 v[16:17], v[16:17], v[16:17], v[0:1] op_sel_hi:[1,1,0]
	v_pk_add_f32 v[124:125], v[126:127], v[124:125]
	v_mov_b32_e32 v16, v127
	v_pk_mul_f32 v[126:127], v[126:127], v[126:127]
	v_mul_f32_e32 v9, v4, v4
	v_mov_b32_e32 v125, v127
	v_pk_add_f32 v[126:127], v[18:19], v[20:21] op_sel:[1,0] op_sel_hi:[0,1]
	v_mov_b32_e32 v127, v9
	v_pk_add_f32 v[4:5], v[16:17], v[4:5]
	v_pk_add_f32 v[124:125], v[124:125], v[126:127]
	s_nop 0
	v_pk_add_f32 v[4:5], v[124:125], v[4:5]
	s_waitcnt vmcnt(3)
	v_lshlrev_b32_e32 v17, 16, v129
	v_lshlrev_b32_e32 v16, 16, v128
	v_and_b32_e32 v129, 0xffff0000, v129
	v_and_b32_e32 v128, 0xffff0000, v128
	v_pk_add_f32 v[18:19], v[16:17], v[128:129]
	v_pk_mul_f32 v[128:129], v[128:129], v[128:129]
	v_pk_add_f32 v[20:21], v[4:5], v[18:19]
	v_pk_fma_f32 v[128:129], v[16:17], v[16:17], v[128:129]
	s_nop 0
	v_add_f32_e32 v0, v5, v128
	v_pk_add_f32 v[4:5], v[128:129], v[0:1] op_sel_hi:[1,0]
	v_and_b32_e32 v128, 0xffff0000, v130
	v_lshlrev_b32_e32 v130, 16, v130
	v_and_b32_e32 v4, 0xffff0000, v131
	v_lshlrev_b32_e32 v131, 16, v131
	v_mov_b32_e32 v16, v130
	v_mov_b32_e32 v17, v128
	v_mul_f32_e32 v0, v130, v130
	v_mov_b32_e32 v129, v131
	v_pk_fma_f32 v[16:17], v[16:17], v[16:17], v[0:1] op_sel_hi:[1,1,0]
	v_pk_add_f32 v[128:129], v[130:131], v[128:129]
	v_mov_b32_e32 v16, v131
	v_pk_mul_f32 v[130:131], v[130:131], v[130:131]
	v_mul_f32_e32 v9, v4, v4
	v_mov_b32_e32 v129, v131
	v_pk_add_f32 v[130:131], v[18:19], v[20:21] op_sel:[1,0] op_sel_hi:[0,1]
	v_mov_b32_e32 v131, v9
	v_pk_add_f32 v[4:5], v[16:17], v[4:5]
	v_pk_add_f32 v[128:129], v[128:129], v[130:131]
	s_nop 0
	v_pk_add_f32 v[4:5], v[128:129], v[4:5]
	s_waitcnt vmcnt(2)
; __device__ __forceinline__ float bf_lo(unsigned w) { return __uint_as_float(w << 16); }
; __device__ __forceinline__ float bf_hi(unsigned w) { return __uint_as_float(w & 0xffff0000u); }
; __device__ __forceinline__ float shx(float v, int o, int lane) { return __int_as_float(__builtin_amdgcn_ds_bpermute((lane ^ o) << 2, __float_as_int(v))); }
; __device__ __forceinline__ void gate_unit(LAS unsigned char* lds, bf16_t* Zg, int ch, const bf16_t* wsb, const float* ln_g, const float* ln_b, const float* b_s, bool dostore = true) {
;     ...
;     {
;         const int row = tid >> 2, part = tid & 3; const bf16_t* src = Zc + (size_t)row * ZLD + COL_VB + part * 8;
;         float s = 0.f, s2 = 0.f;
; #pragma unroll 8
;         for (int i = 0; i < 32; ++i) { const u32x4 w = *(const u32x4*)(src + i * 32);
; #pragma unroll
;             for (int e = 0; e < 4; ++e) { const float a = bf_lo(w[e]), b = bf_hi(w[e]); s += a + b; s2 += a * a + b * b; } }
;         s += shx(s, 1, lane); s += shx(s, 2, lane); s2 += shx(s2, 1, lane); s2 += shx(s2, 2, lane);
;         const float mean = s * (1.0f / 1024.0f); const float var = fmaxf(s2 * (1.0f / 1024.0f) - mean * mean, 0.f);
;         if (part == 0) { stats[row * 2] = mean; stats[row * 2 + 1] = 1.0f / sqrtf(var + EPS); }
;     }
	v_lshlrev_b32_e32 v17, 16, v133
	v_lshlrev_b32_e32 v16, 16, v132
	v_and_b32_e32 v133, 0xffff0000, v133
	v_and_b32_e32 v132, 0xffff0000, v132
	v_pk_add_f32 v[18:19], v[16:17], v[132:133]
	v_pk_mul_f32 v[132:133], v[132:133], v[132:133]
	v_pk_add_f32 v[20:21], v[4:5], v[18:19]
	v_pk_fma_f32 v[132:133], v[16:17], v[16:17], v[132:133]
	s_nop 0
	v_add_f32_e32 v0, v5, v132
	v_pk_add_f32 v[4:5], v[132:133], v[0:1] op_sel_hi:[1,0]
	v_and_b32_e32 v132, 0xffff0000, v134
	v_lshlrev_b32_e32 v134, 16, v134
	v_and_b32_e32 v4, 0xffff0000, v135
	v_lshlrev_b32_e32 v135, 16, v135
	v_mov_b32_e32 v16, v134
	v_mov_b32_e32 v17, v132
	v_mul_f32_e32 v0, v134, v134
	v_mov_b32_e32 v133, v135
	v_pk_fma_f32 v[16:17], v[16:17], v[16:17], v[0:1] op_sel_hi:[1,1,0]
	v_pk_add_f32 v[132:133], v[134:135], v[132:133]
	v_mov_b32_e32 v16, v135
	v_pk_mul_f32 v[134:135], v[134:135], v[134:135]
	v_mul_f32_e32 v9, v4, v4
	v_mov_b32_e32 v133, v135
	v_pk_add_f32 v[134:135], v[18:19], v[20:21] op_sel:[1,0] op_sel_hi:[0,1]
	v_mov_b32_e32 v135, v9
	v_pk_add_f32 v[4:5], v[16:17], v[4:5]
	v_pk_add_f32 v[132:133], v[132:133], v[134:135]
	s_nop 0
	v_pk_add_f32 v[4:5], v[132:133], v[4:5]
	s_waitcnt vmcnt(1)
	v_lshlrev_b32_e32 v17, 16, v137
	v_lshlrev_b32_e32 v16, 16, v136
	v_and_b32_e32 v137, 0xffff0000, v137
	v_and_b32_e32 v136, 0xffff0000, v136
	v_pk_add_f32 v[18:19], v[16:17], v[136:137]
	v_pk_mul_f32 v[136:137], v[136:137], v[136:137]
	v_pk_add_f32 v[20:21], v[4:5], v[18:19]
	v_pk_fma_f32 v[136:137], v[16:17], v[16:17], v[136:137]
	s_nop 0
	v_add_f32_e32 v0, v5, v136
	v_pk_add_f32 v[4:5], v[136:137], v[0:1] op_sel_hi:[1,0]
	v_and_b32_e32 v136, 0xffff0000, v138
	v_lshlrev_b32_e32 v138, 16, v138
	v_and_b32_e32 v4, 0xffff0000, v139
	v_lshlrev_b32_e32 v139, 16, v139
	v_mov_b32_e32 v16, v138
	v_mov_b32_e32 v17, v136
	v_mul_f32_e32 v0, v138, v138
	v_mov_b32_e32 v137, v139
	v_pk_fma_f32 v[16:17], v[16:17], v[16:17], v[0:1] op_sel_hi:[1,1,0]
	v_pk_add_f32 v[136:137], v[138:139], v[136:137]
	v_mov_b32_e32 v16, v139
	v_pk_mul_f32 v[138:139], v[138:139], v[138:139]
	v_mul_f32_e32 v9, v4, v4
	v_mov_b32_e32 v137, v139
	v_pk_add_f32 v[138:139], v[18:19], v[20:21] op_sel:[1,0] op_sel_hi:[0,1]
	v_mov_b32_e32 v139, v9
	v_pk_add_f32 v[4:5], v[16:17], v[4:5]
	v_pk_add_f32 v[136:137], v[136:137], v[138:139]
	s_nop 0
	v_pk_add_f32 v[4:5], v[136:137], v[4:5]
	s_waitcnt vmcnt(0)
	v_lshlrev_b32_e32 v15, 16, v141
	v_lshlrev_b32_e32 v14, 16, v140
	v_and_b32_e32 v141, 0xffff0000, v141
	v_and_b32_e32 v140, 0xffff0000, v140
	v_pk_add_f32 v[16:17], v[14:15], v[140:141]
	v_pk_mul_f32 v[140:141], v[140:141], v[140:141]
	v_pk_add_f32 v[18:19], v[4:5], v[16:17]
	v_pk_fma_f32 v[140:141], v[14:15], v[14:15], v[140:141]
	s_nop 0
	v_add_f32_e32 v0, v5, v140
	v_pk_add_f32 v[4:5], v[140:141], v[0:1] op_sel_hi:[1,0]
	v_and_b32_e32 v140, 0xffff0000, v142
	v_lshlrev_b32_e32 v142, 16, v142
	v_and_b32_e32 v4, 0xffff0000, v143
	v_lshlrev_b32_e32 v143, 16, v143
	v_mov_b32_e32 v14, v142
	v_mov_b32_e32 v15, v140
	v_mul_f32_e32 v0, v142, v142
	v_mov_b32_e32 v141, v143
	v_pk_fma_f32 v[14:15], v[14:15], v[14:15], v[0:1] op_sel_hi:[1,1,0]
	v_pk_add_f32 v[140:141], v[142:143], v[140:141]
	v_mov_b32_e32 v14, v143
	v_pk_mul_f32 v[142:143], v[142:143], v[142:143]
	v_mul_f32_e32 v9, v4, v4
	v_mov_b32_e32 v141, v143
	v_pk_add_f32 v[142:143], v[16:17], v[18:19] op_sel:[1,0] op_sel_hi:[0,1]
	v_mov_b32_e32 v143, v9
	v_pk_add_f32 v[4:5], v[14:15], v[4:5]
	v_pk_add_f32 v[140:141], v[140:141], v[142:143]
	s_nop 0
	v_pk_add_f32 v[4:5], v[140:141], v[4:5]
	s_cbranch_scc0 .LBB0_179
	v_and_b32_e32 v0, 63, v6
	v_lshlrev_b32_e32 v2, 2, v0
	v_xor_b32_e32 v3, 4, v2
	ds_bpermute_b32 v9, v3, v4
	ds_bpermute_b32 v3, v3, v5
	v_xor_b32_e32 v10, 8, v2
	v_readfirstlane_b32 s10, v6
	v_cmp_eq_u32_e32 vcc, 0, v8
	s_waitcnt lgkmcnt(1)
	v_add_f32_e32 v2, v4, v9
	s_waitcnt lgkmcnt(0)
	v_add_f32_e32 v4, v5, v3
	ds_bpermute_b32 v3, v10, v2
	ds_bpermute_b32 v5, v10, v4
	s_and_saveexec_b64 s[74:75], vcc
	s_cbranch_execz .LBB0_182
	s_waitcnt lgkmcnt(1)
	v_add_f32_e32 v2, v2, v3
	v_mul_f32_e32 v2, 0x3a800000, v2
	s_waitcnt lgkmcnt(0)
	v_add_f32_e32 v4, v4, v5
	v_mul_f32_e32 v3, v2, v2
	s_mov_b32 s4, 0x3a800000
	v_fma_f32 v3, v4, s4, -v3
	v_max_f32_e32 v3, 0, v3
	v_add_f32_e32 v3, 0x358637bd, v3
	v_mul_f32_e32 v4, 0x4f800000, v3
	v_cmp_gt_f32_e32 vcc, s36, v3
	v_lshl_add_u32 v7, v7, 3, 0
	s_nop 0
	v_cndmask_b32_e32 v3, v3, v4, vcc
	v_sqrt_f32_e32 v4, v3
	s_nop 0
	v_add_u32_e32 v5, -1, v4
	v_fma_f32 v8, -v5, v4, v3
	v_cmp_ge_f32_e64 s[4:5], 0, v8
	v_add_u32_e32 v8, 1, v4
	s_nop 0
	v_cndmask_b32_e64 v5, v4, v5, s[4:5]
	v_fma_f32 v4, -v8, v4, v3
	v_cmp_lt_f32_e64 s[4:5], 0, v4
	s_nop 1
	v_cndmask_b32_e64 v4, v5, v8, s[4:5]
	v_mul_f32_e32 v5, 0x37800000, v4
	v_cndmask_b32_e32 v4, v4, v5, vcc
	v_cmp_class_f32_e32 vcc, v3, v205
	s_nop 1
	v_cndmask_b32_e32 v3, v4, v3, vcc
	v_div_scale_f32 v4, s[4:5], v3, v3, 1.0
	v_rcp_f32_e32 v5, v4
	s_nop 0
	v_fma_f32 v8, -v4, v5, 1.0
	v_fmac_f32_e32 v5, v8, v5
	v_div_scale_f32 v8, vcc, 1.0, v3, 1.0
	v_mul_f32_e32 v9, v8, v5
	v_fma_f32 v10, -v4, v9, v8
	v_fmac_f32_e32 v9, v10, v5
	v_fma_f32 v4, -v4, v9, v8
	v_div_fmas_f32 v4, v4, v5, v9
	v_div_fixup_f32 v3, v4, v3, 1.0
	ds_write_b64 v7, v[2:3]

; #define LAS __attribute__((address_space(3)))
; __device__ __forceinline__ void gate_unit(LAS unsigned char* lds, bf16_t* Zg, int ch, const bf16_t* wsb, const float* ln_g, const float* ln_b, const float* b_s, bool dostore = true) {
;     ...
;     for (int g = 0; g < 8; ++g) {
; #pragma unroll
;         for (int i = 0; i < 4; ++i) { const int p = tid + 512 * i, q = p >> 4, c = p & 15; const int col = g * 128 + c * 8;
;             const u32x4 w = *(const u32x4*)(Zc + (size_t)q * ZLD + COL_VB + col);
;             const float mean = stats[q * 2], rstd = stats[q * 2 + 1];
;             const f32x4 g0 = *(const f32x4*)(ln_g + col), g1 = *(const f32x4*)(ln_g + col + 4), b0 = *(const f32x4*)(ln_b + col), b1 = *(const f32x4*)(ln_b + col + 4);
;             float v[8] = {bf_lo(w.x), bf_hi(w.x), bf_lo(w.y), bf_hi(w.y), bf_lo(w.z), bf_hi(w.z), bf_lo(w.w), bf_hi(w.w)};
;             const float gg[8] = {g0.x, g0.y, g0.z, g0.w, g1.x, g1.y, g1.z, g1.w}, bb[8] = {b0.x, b0.y, b0.z, b0.w, b1.x, b1.y, b1.z, b1.w};
; #pragma unroll
;             for (int e = 0; e < 8; ++e) vnT[(c * 8 + e) * 136 + q] = (bf16_t)f2bf((v[e] - mean) * rstd * gg[e] + bb[e]); }
;         __syncthreads();
;         f32x16 acc[2]; acc[0] = f32x16{}; acc[1] = f32x16{};
;         const bf16_t* ap = wsb + (size_t)g * 16384 + (32 * pt + r32) * 128 + 8 * hi;
; #pragma unroll
;         for (int ks = 0; ks < 8; ++ks) { const bf16x8 a = *(const bf16x8*)(ap + 16 * ks);
; #pragma unroll
;             for (int j = 0; j < 2; ++j) { const bf16x8 b = *(const LAS bf16x8*)(vnT + (32 * (kt0 + j) + r32) * 136 + 16 * ks + 8 * hi);
;                 acc[j] = __builtin_amdgcn_mfma_f32_32x32x16_bf16(a, b, acc[j], 0, 0, 0); } }
;         LAS float* st = (LAS float*)(lds + 40960);
; #pragma unroll
;         for (int j = 0; j < 2; ++j)
; #pragma unroll
;             for (int r = 0; r < 16; ++r) { const int p = 32 * pt + crow(r, hi); st[p * 132 + 32 * (kt0 + j) + r32] = acc[j][r] + b_s[g * 128 + p]; }
;         __syncthreads();
; #pragma unroll
;         for (int i = 0; i < 4; ++i) { const int p = (tid >> 4) + 32 * i, c8 = (tid & 15) * 8; bf16_t* zr = Zc + (size_t)p * ZLD + g * 128 + c8;
;             const u32x4 uw = *(const u32x4*)(zr + COL_U), gw = *(const u32x4*)(zr + COL_GB);
;             const f32x4 s0 = *(const LAS f32x4*)(st + p * 132 + c8), s1 = *(const LAS f32x4*)(st + p * 132 + c8 + 4);
.LBB0_183:
	v_lshl_add_u64 v[58:59], v[46:47], 0, s[4:5]
	v_add_co_u32_e32 v60, vcc, 0x5a02000, v58
	ds_read_b64 v[22:23], v36
	s_nop 0
	v_addc_co_u32_e32 v61, vcc, 0, v59, vcc
	global_load_dwordx4 v[18:21], v[60:61], off offset:2048
	global_load_dwordx4 v[2:5], v[50:51], off
	global_load_dwordx4 v[10:13], v[50:51], off offset:-16
	global_load_dwordx4 v[6:9], v[54:55], off
	global_load_dwordx4 v[14:17], v[54:55], off offset:-16
	v_ashrrev_i32_e32 v35, 31, v34
	s_mov_b32 s10, 0x5a03000
	s_mov_b64 s[16:17], 0x8000
	v_lshl_add_u64 v[50:51], v[50:51], 0, s[60:61]
	v_lshl_add_u64 v[54:55], v[54:55], 0, s[60:61]
	v_lshl_add_u64 v[80:81], v[56:57], 0, s[4:5]
	global_load_dwordx4 v[80:83], v[80:81], off
	v_lshl_add_u64 v[84:85], v[52:53], 0, s[4:5]
	global_load_dwordx4 v[84:87], v[84:85], off
	v_lshl_add_u64 v[88:89], v[48:49], 0, s[4:5]
	global_load_dwordx4 v[88:91], v[88:89], off
	global_load_dwordx4 v[92:95], v[44:45], off
	global_load_dwordx4 v[96:99], v[44:45], off offset:32
	global_load_dwordx4 v[100:103], v[44:45], off offset:64
	global_load_dwordx4 v[104:107], v[44:45], off offset:96
	global_load_dwordx4 v[108:111], v[44:45], off offset:128
	global_load_dwordx4 v[112:115], v[44:45], off offset:160
	global_load_dwordx4 v[116:119], v[44:45], off offset:192
	global_load_dwordx4 v[120:123], v[44:45], off offset:224
	v_lshl_add_u64 v[124:125], v[34:35], 2, s[20:21]
	global_load_dwordx4 v[126:129], v[124:125], off
	global_load_dwordx4 v[130:133], v[124:125], off offset:32
	global_load_dwordx4 v[134:137], v[124:125], off offset:64
	global_load_dwordx4 v[138:141], v[124:125], off offset:96
	v_add_co_u32_e32 v174, vcc, 0x5a03000, v58
	s_nop 1
	v_addc_co_u32_e32 v175, vcc, 0, v59, vcc
	global_load_dwordx4 v[142:145], v[174:175], off offset:-4096
	global_load_dwordx4 v[146:149], v[174:175], off
	v_add_co_u32_e32 v174, vcc, 0x5a93000, v58
	s_nop 1
	v_addc_co_u32_e32 v175, vcc, 0, v59, vcc
	global_load_dwordx4 v[150:153], v[174:175], off offset:-4096
	global_load_dwordx4 v[154:157], v[174:175], off
	v_add_co_u32_e32 v174, vcc, 0x5b23000, v58
	s_nop 1
	v_addc_co_u32_e32 v175, vcc, 0, v59, vcc
	global_load_dwordx4 v[158:161], v[174:175], off offset:-4096
	global_load_dwordx4 v[162:165], v[174:175], off
	v_add_co_u32_e32 v174, vcc, 0x5bb3000, v58
	s_nop 1
	v_addc_co_u32_e32 v175, vcc, 0, v59, vcc
	global_load_dwordx4 v[166:169], v[174:175], off offset:-4096
	global_load_dwordx4 v[170:173], v[174:175], off
	s_waitcnt vmcnt(27)
	v_lshlrev_b32_e32 v24, 16, v18
	s_waitcnt lgkmcnt(0)
	v_sub_f32_e32 v24, v24, v22
	v_and_b32_e32 v18, 0xffff0000, v18
	v_mul_f32_e32 v24, v23, v24
	s_waitcnt vmcnt(23)
	v_fma_f32 v24, v10, v24, v14
	v_sub_f32_e32 v18, v18, v22
	v_bfe_u32 v28, v24, 16, 1
	v_mul_f32_e32 v18, v23, v18
	v_add3_u32 v24, v24, v28, s38
	v_fma_f32 v18, v11, v18, v15
	ds_write_b16_d16_hi v0, v24 offset:2048
	v_bfe_u32 v24, v18, 16, 1
	v_lshlrev_b32_e32 v25, 16, v19
	v_add3_u32 v18, v18, v24, s38
	ds_write_b16_d16_hi v0, v18 offset:2320
	v_sub_f32_e32 v18, v25, v22
	v_mul_f32_e32 v18, v23, v18
	v_fma_f32 v18, v12, v18, v16
	v_bfe_u32 v24, v18, 16, 1
	v_and_b32_e32 v19, 0xffff0000, v19
	v_add3_u32 v18, v18, v24, s38
	ds_write_b16_d16_hi v0, v18 offset:2592
	v_sub_f32_e32 v18, v19, v22
	v_mul_f32_e32 v18, v23, v18
	v_fma_f32 v18, v13, v18, v17
	v_bfe_u32 v19, v18, 16, 1
	v_lshlrev_b32_e32 v26, 16, v20
	v_add3_u32 v18, v18, v19, s38
	ds_write_b16_d16_hi v0, v18 offset:2864
	v_sub_f32_e32 v18, v26, v22
	v_mul_f32_e32 v18, v23, v18
	v_fma_f32 v18, v2, v18, v6
	v_bfe_u32 v19, v18, 16, 1
	v_and_b32_e32 v20, 0xffff0000, v20
	v_add3_u32 v18, v18, v19, s38
	ds_write_b16_d16_hi v0, v18 offset:3136
	v_sub_f32_e32 v18, v20, v22
	v_mul_f32_e32 v18, v23, v18
	v_fma_f32 v18, v3, v18, v7
	v_bfe_u32 v19, v18, 16, 1
	v_lshlrev_b32_e32 v27, 16, v21
	v_add3_u32 v18, v18, v19, s38
	ds_write_b16_d16_hi v0, v18 offset:3408
	v_sub_f32_e32 v18, v27, v22
	v_mul_f32_e32 v18, v23, v18
	v_fma_f32 v18, v4, v18, v8
	v_bfe_u32 v19, v18, 16, 1
	v_and_b32_e32 v21, 0xffff0000, v21
	v_add3_u32 v18, v18, v19, s38
	ds_write_b16_d16_hi v0, v18 offset:3680
	v_sub_f32_e32 v18, v21, v22
	v_mul_f32_e32 v18, v23, v18
	v_fma_f32 v18, v5, v18, v9
	v_bfe_u32 v19, v18, 16, 1
	v_add3_u32 v18, v18, v19, s38
	ds_write_b16_d16_hi v0, v18 offset:3952
	s_waitcnt vmcnt(22)
	v_mov_b64_e32 v[18:19], v[80:81]
	v_mov_b64_e32 v[20:21], v[82:83]
	ds_read_b64 v[22:23], v38
	v_lshlrev_b32_e32 v24, 16, v18
	s_waitcnt lgkmcnt(0)
	v_sub_f32_e32 v24, v24, v22
	v_and_b32_e32 v18, 0xffff0000, v18
	v_mul_f32_e32 v24, v23, v24
	v_fma_f32 v24, v10, v24, v14
	v_sub_f32_e32 v18, v18, v22
	v_bfe_u32 v28, v24, 16, 1
	v_mul_f32_e32 v18, v23, v18
	v_add3_u32 v24, v24, v28, s38
	v_fma_f32 v18, v11, v18, v15
	ds_write_b16_d16_hi v41, v24 offset:2048
	v_bfe_u32 v24, v18, 16, 1
	v_lshlrev_b32_e32 v25, 16, v19
	v_add3_u32 v18, v18, v24, s38
	ds_write_b16_d16_hi v41, v18 offset:2320
	v_sub_f32_e32 v18, v25, v22
	v_mul_f32_e32 v18, v23, v18
	v_fma_f32 v18, v12, v18, v16
	v_bfe_u32 v24, v18, 16, 1
	v_and_b32_e32 v19, 0xffff0000, v19
	v_add3_u32 v18, v18, v24, s38
	ds_write_b16_d16_hi v41, v18 offset:2592
	v_sub_f32_e32 v18, v19, v22
	v_mul_f32_e32 v18, v23, v18
	v_fma_f32 v18, v13, v18, v17
	v_bfe_u32 v19, v18, 16, 1
	v_lshlrev_b32_e32 v26, 16, v20
	v_add3_u32 v18, v18, v19, s38
	ds_write_b16_d16_hi v41, v18 offset:2864
	v_sub_f32_e32 v18, v26, v22
	v_mul_f32_e32 v18, v23, v18
	v_fma_f32 v18, v2, v18, v6
	v_bfe_u32 v19, v18, 16, 1
	v_and_b32_e32 v20, 0xffff0000, v20
	v_add3_u32 v18, v18, v19, s38
	ds_write_b16_d16_hi v41, v18 offset:3136
	v_sub_f32_e32 v18, v20, v22
	v_mul_f32_e32 v18, v23, v18
	v_fma_f32 v18, v3, v18, v7
	v_bfe_u32 v19, v18, 16, 1
	v_lshlrev_b32_e32 v27, 16, v21
	v_add3_u32 v18, v18, v19, s38
	ds_write_b16_d16_hi v41, v18 offset:3408
	v_sub_f32_e32 v18, v27, v22
	v_mul_f32_e32 v18, v23, v18
	v_fma_f32 v18, v4, v18, v8
	v_bfe_u32 v19, v18, 16, 1
	v_and_b32_e32 v21, 0xffff0000, v21
	v_add3_u32 v18, v18, v19, s38
	ds_write_b16_d16_hi v41, v18 offset:3680
	v_sub_f32_e32 v18, v21, v22
	v_mul_f32_e32 v18, v23, v18
	v_fma_f32 v18, v5, v18, v9
	v_bfe_u32 v19, v18, 16, 1
	v_add3_u32 v18, v18, v19, s38
	ds_write_b16_d16_hi v41, v18 offset:3952
	s_waitcnt vmcnt(21)
; __device__ __forceinline__ float bf_lo(unsigned w) { return __uint_as_float(w << 16); }
; __device__ __forceinline__ float bf_hi(unsigned w) { return __uint_as_float(w & 0xffff0000u); }
; #define LAS __attribute__((address_space(3)))
; __device__ __forceinline__ unsigned f2bf(float f) { unsigned u = __builtin_bit_cast(unsigned, f); return (u + 0x7fffu + ((u >> 16) & 1u)) >> 16; }
; __device__ __forceinline__ void gate_unit(LAS unsigned char* lds, bf16_t* Zg, int ch, const bf16_t* wsb, const float* ln_g, const float* ln_b, const float* b_s, bool dostore = true) {
;     ...
;         for (int i = 0; i < 4; ++i) { const int p = tid + 512 * i, q = p >> 4, c = p & 15; const int col = g * 128 + c * 8;
;             const u32x4 w = *(const u32x4*)(Zc + (size_t)q * ZLD + COL_VB + col);
;             const float mean = stats[q * 2], rstd = stats[q * 2 + 1];
;             const f32x4 g0 = *(const f32x4*)(ln_g + col), g1 = *(const f32x4*)(ln_g + col + 4), b0 = *(const f32x4*)(ln_b + col), b1 = *(const f32x4*)(ln_b + col + 4);
;             float v[8] = {bf_lo(w.x), bf_hi(w.x), bf_lo(w.y), bf_hi(w.y), bf_lo(w.z), bf_hi(w.z), bf_lo(w.w), bf_hi(w.w)};
;             const float gg[8] = {g0.x, g0.y, g0.z, g0.w, g1.x, g1.y, g1.z, g1.w}, bb[8] = {b0.x, b0.y, b0.z, b0.w, b1.x, b1.y, b1.z, b1.w};
; #pragma unroll
;             for (int e = 0; e < 8; ++e) vnT[(c * 8 + e) * 136 + q] = (bf16_t)f2bf((v[e] - mean) * rstd * gg[e] + bb[e]); }
;         __syncthreads();
;         f32x16 acc[2]; acc[0] = f32x16{}; acc[1] = f32x16{};
;         const bf16_t* ap = wsb + (size_t)g * 16384 + (32 * pt + r32) * 128 + 8 * hi;
; #pragma unroll
;         for (int ks = 0; ks < 8; ++ks) { const bf16x8 a = *(const bf16x8*)(ap + 16 * ks);
; #pragma unroll
;             for (int j = 0; j < 2; ++j) { const bf16x8 b = *(const LAS bf16x8*)(vnT + (32 * (kt0 + j) + r32) * 136 + 16 * ks + 8 * hi);
;                 acc[j] = __builtin_amdgcn_mfma_f32_32x32x16_bf16(a, b, acc[j], 0, 0, 0); } }
	v_mov_b64_e32 v[18:19], v[84:85]
	v_mov_b64_e32 v[20:21], v[86:87]
	ds_read_b64 v[22:23], v40
	v_lshlrev_b32_e32 v24, 16, v18
	s_waitcnt lgkmcnt(0)
	v_sub_f32_e32 v24, v24, v22
	v_and_b32_e32 v18, 0xffff0000, v18
	v_mul_f32_e32 v24, v23, v24
	v_fma_f32 v24, v10, v24, v14
	v_sub_f32_e32 v18, v18, v22
	v_bfe_u32 v28, v24, 16, 1
	v_mul_f32_e32 v18, v23, v18
	v_add3_u32 v24, v24, v28, s38
	v_fma_f32 v18, v11, v18, v15
	ds_write_b16_d16_hi v43, v24 offset:2048
	v_bfe_u32 v24, v18, 16, 1
	v_lshlrev_b32_e32 v25, 16, v19
	v_add3_u32 v18, v18, v24, s38
	ds_write_b16_d16_hi v43, v18 offset:2320
	v_sub_f32_e32 v18, v25, v22
	v_mul_f32_e32 v18, v23, v18
	v_fma_f32 v18, v12, v18, v16
	v_bfe_u32 v24, v18, 16, 1
	v_and_b32_e32 v19, 0xffff0000, v19
	v_add3_u32 v18, v18, v24, s38
	ds_write_b16_d16_hi v43, v18 offset:2592
	v_sub_f32_e32 v18, v19, v22
	v_mul_f32_e32 v18, v23, v18
	v_fma_f32 v18, v13, v18, v17
	v_bfe_u32 v19, v18, 16, 1
	v_lshlrev_b32_e32 v26, 16, v20
	v_add3_u32 v18, v18, v19, s38
	ds_write_b16_d16_hi v43, v18 offset:2864
	v_sub_f32_e32 v18, v26, v22
	v_mul_f32_e32 v18, v23, v18
	v_fma_f32 v18, v2, v18, v6
	v_bfe_u32 v19, v18, 16, 1
	v_and_b32_e32 v20, 0xffff0000, v20
	v_add3_u32 v18, v18, v19, s38
	ds_write_b16_d16_hi v43, v18 offset:3136
	v_sub_f32_e32 v18, v20, v22
	v_mul_f32_e32 v18, v23, v18
	v_fma_f32 v18, v3, v18, v7
	v_bfe_u32 v19, v18, 16, 1
	v_lshlrev_b32_e32 v27, 16, v21
	v_add3_u32 v18, v18, v19, s38
	ds_write_b16_d16_hi v43, v18 offset:3408
	v_sub_f32_e32 v18, v27, v22
	v_mul_f32_e32 v18, v23, v18
	v_fma_f32 v18, v4, v18, v8
	v_bfe_u32 v19, v18, 16, 1
	v_and_b32_e32 v21, 0xffff0000, v21
	v_add3_u32 v18, v18, v19, s38
	ds_write_b16_d16_hi v43, v18 offset:3680
	v_sub_f32_e32 v18, v21, v22
	v_mul_f32_e32 v18, v23, v18
	v_fma_f32 v18, v5, v18, v9
	v_bfe_u32 v19, v18, 16, 1
	v_add3_u32 v18, v18, v19, s38
	ds_write_b16_d16_hi v43, v18 offset:3952
	s_waitcnt vmcnt(20)
	v_mov_b64_e32 v[18:19], v[88:89]
	v_mov_b64_e32 v[20:21], v[90:91]
	ds_read_b64 v[22:23], v42
	s_add_u32 s4, s4, 0x100
	s_addc_u32 s5, s5, 0
	s_cmpk_lg_i32 s4, 0x800
	v_lshlrev_b32_e32 v24, 16, v18
	s_waitcnt lgkmcnt(0)
	v_sub_f32_e32 v24, v24, v22
	v_mul_f32_e32 v24, v23, v24
	v_fma_f32 v10, v10, v24, v14
	v_bfe_u32 v14, v10, 16, 1
	v_and_b32_e32 v18, 0xffff0000, v18
	v_add3_u32 v10, v10, v14, s38
	ds_write_b16_d16_hi v62, v10 offset:2048
	v_sub_f32_e32 v10, v18, v22
	v_mul_f32_e32 v10, v23, v10
	v_fma_f32 v10, v11, v10, v15
	v_bfe_u32 v11, v10, 16, 1
	v_lshlrev_b32_e32 v25, 16, v19
	v_add3_u32 v10, v10, v11, s38
	ds_write_b16_d16_hi v62, v10 offset:2320
	v_sub_f32_e32 v10, v25, v22
	v_mul_f32_e32 v10, v23, v10
	v_fma_f32 v10, v12, v10, v16
	v_bfe_u32 v11, v10, 16, 1
	v_and_b32_e32 v19, 0xffff0000, v19
	v_add3_u32 v10, v10, v11, s38
	ds_write_b16_d16_hi v62, v10 offset:2592
	v_sub_f32_e32 v10, v19, v22
	v_mul_f32_e32 v10, v23, v10
	v_fmac_f32_e32 v17, v13, v10
	v_bfe_u32 v10, v17, 16, 1
	v_lshlrev_b32_e32 v26, 16, v20
	v_add3_u32 v10, v17, v10, s38
	ds_write_b16_d16_hi v62, v10 offset:2864
	v_sub_f32_e32 v10, v26, v22
	v_mul_f32_e32 v10, v23, v10
	v_fma_f32 v2, v2, v10, v6
	v_bfe_u32 v6, v2, 16, 1
	v_and_b32_e32 v20, 0xffff0000, v20
	v_add3_u32 v2, v2, v6, s38
	ds_write_b16_d16_hi v62, v2 offset:3136
	v_sub_f32_e32 v2, v20, v22
	v_mul_f32_e32 v2, v23, v2
	v_fma_f32 v2, v3, v2, v7
	v_bfe_u32 v3, v2, 16, 1
	v_lshlrev_b32_e32 v27, 16, v21
	v_add3_u32 v2, v2, v3, s38
	ds_write_b16_d16_hi v62, v2 offset:3408
	v_sub_f32_e32 v2, v27, v22
	v_mul_f32_e32 v2, v23, v2
	v_fma_f32 v2, v4, v2, v8
	v_bfe_u32 v3, v2, 16, 1
	v_and_b32_e32 v21, 0xffff0000, v21
	v_add3_u32 v2, v2, v3, s38
	ds_write_b16_d16_hi v62, v2 offset:3680
	v_sub_f32_e32 v2, v21, v22
	v_mul_f32_e32 v2, v23, v2
	v_fmac_f32_e32 v9, v5, v2
	v_bfe_u32 v2, v9, 16, 1
	v_add3_u32 v2, v9, v2, s38
	ds_write_b16_d16_hi v62, v2 offset:3952
	s_waitcnt lgkmcnt(0)
	s_barrier
	ds_read_b128 v[6:9], v63 offset:2048
	ds_read_b128 v[68:71], v63 offset:2080
	s_waitcnt vmcnt(12) lgkmcnt(1)
	v_mfma_f32_32x32x16_bf16 v[18:33], v[92:95], v[6:9], 0
	ds_read_b128 v[6:9], v64 offset:2048
	ds_read_b128 v[72:75], v64 offset:2080
	s_waitcnt lgkmcnt(1)
	v_mfma_f32_32x32x16_bf16 v[2:17], v[92:95], v[6:9], 0
	v_mfma_f32_32x32x16_bf16 v[18:33], v[96:99], v[68:71], v[18:33]
	s_waitcnt lgkmcnt(0)
	v_mfma_f32_32x32x16_bf16 v[2:17], v[96:99], v[72:75], v[2:17]
	ds_read_b128 v[72:75], v63 offset:2112
	s_waitcnt lgkmcnt(0)
	v_mfma_f32_32x32x16_bf16 v[18:33], v[100:103], v[72:75], v[18:33]
	ds_read_b128 v[72:75], v64 offset:2112
	s_waitcnt lgkmcnt(0)
	v_mfma_f32_32x32x16_bf16 v[2:17], v[100:103], v[72:75], v[2:17]
	ds_read_b128 v[72:75], v63 offset:2144
	s_waitcnt lgkmcnt(0)
	v_mfma_f32_32x32x16_bf16 v[18:33], v[104:107], v[72:75], v[18:33]
	ds_read_b128 v[72:75], v64 offset:2144
	s_waitcnt lgkmcnt(0)
	v_mfma_f32_32x32x16_bf16 v[2:17], v[104:107], v[72:75], v[2:17]
	ds_read_b128 v[72:75], v63 offset:2176
	s_waitcnt lgkmcnt(0)
	v_mfma_f32_32x32x16_bf16 v[18:33], v[108:111], v[72:75], v[18:33]
	ds_read_b128 v[72:75], v64 offset:2176
	s_waitcnt lgkmcnt(0)
	v_mfma_f32_32x32x16_bf16 v[2:17], v[108:111], v[72:75], v[2:17]
	ds_read_b128 v[72:75], v63 offset:2208
	s_waitcnt lgkmcnt(0)
	v_mfma_f32_32x32x16_bf16 v[18:33], v[112:115], v[72:75], v[18:33]
	ds_read_b128 v[72:75], v64 offset:2208
	s_waitcnt lgkmcnt(0)
	v_mfma_f32_32x32x16_bf16 v[2:17], v[112:115], v[72:75], v[2:17]
	ds_read_b128 v[72:75], v63 offset:2240
	s_waitcnt lgkmcnt(0)
	v_mfma_f32_32x32x16_bf16 v[18:33], v[116:119], v[72:75], v[18:33]
	ds_read_b128 v[72:75], v64 offset:2240
	s_waitcnt lgkmcnt(0)
	v_mfma_f32_32x32x16_bf16 v[2:17], v[116:119], v[72:75], v[2:17]
	ds_read_b128 v[72:75], v63 offset:2272
	v_lshl_add_u64 v[44:45], v[44:45], 0, s[16:17]
	s_waitcnt lgkmcnt(0)
; __device__ __forceinline__ unsigned cvt_pk_bf16(float lo, float hi) { f32x2 v = {lo, hi}; bf16x2_t b = __builtin_convertvector(v, bf16x2_t); return __builtin_bit_cast(unsigned, b); }
; __device__ __forceinline__ float bf_lo(unsigned w) { return __uint_as_float(w << 16); }
; __device__ __forceinline__ float bf_hi(unsigned w) { return __uint_as_float(w & 0xffff0000u); }
; __device__ __forceinline__ float sigmoidf_fast(float x) { return __builtin_amdgcn_rcpf(1.0f + __builtin_amdgcn_exp2f(-1.4426950408889634f * x)); }
; #define LAS __attribute__((address_space(3)))
; __device__ __forceinline__ int crow(int r, int hi) { return (r & 3) + 8 * (r >> 2) + 4 * hi; }
; __device__ __forceinline__ void gate_unit(LAS unsigned char* lds, bf16_t* Zg, int ch, const bf16_t* wsb, const float* ln_g, const float* ln_b, const float* b_s, bool dostore = true) {
;     ...
;         LAS float* st = (LAS float*)(lds + 40960);
; #pragma unroll
;         for (int j = 0; j < 2; ++j)
; #pragma unroll
;             for (int r = 0; r < 16; ++r) { const int p = 32 * pt + crow(r, hi); st[p * 132 + 32 * (kt0 + j) + r32] = acc[j][r] + b_s[g * 128 + p]; }
;         __syncthreads();
; #pragma unroll
;         for (int i = 0; i < 4; ++i) { const int p = (tid >> 4) + 32 * i, c8 = (tid & 15) * 8; bf16_t* zr = Zc + (size_t)p * ZLD + g * 128 + c8;
;             const u32x4 uw = *(const u32x4*)(zr + COL_U), gw = *(const u32x4*)(zr + COL_GB);
;             const f32x4 s0 = *(const LAS f32x4*)(st + p * 132 + c8), s1 = *(const LAS f32x4*)(st + p * 132 + c8 + 4);
;             const float sv[8] = {s0.x, s0.y, s0.z, s0.w, s1.x, s1.y, s1.z, s1.w}; u32x4 ow;
; #pragma unroll
;             for (int e = 0; e < 4; ++e) { const float u0 = bf_lo(uw[e]), u1 = bf_hi(uw[e]), g0 = bf_lo(gw[e]), g1 = bf_hi(gw[e]);
;                 ow[e] = cvt_pk_bf16(u0 * sv[2 * e] * g0 * sigmoidf_fast(g0), u1 * sv[2 * e + 1] * g1 * sigmoidf_fast(g1)); }
	v_mfma_f32_32x32x16_bf16 v[18:33], v[120:123], v[72:75], v[18:33]
	ds_read_b128 v[72:75], v64 offset:2272
	s_waitcnt lgkmcnt(0)
	v_mfma_f32_32x32x16_bf16 v[2:17], v[120:123], v[72:75], v[2:17]
	v_add_u32_e32 v35, 0xa000, v65
	v_add_u32_e32 v34, 0x80, v34
	s_waitcnt vmcnt(11)
	s_nop 5
	v_add_f32_e32 v18, v18, v126
	v_add_f32_e32 v19, v19, v127
	ds_write2_b32 v35, v18, v19 offset1:132
	v_add_f32_e32 v18, v20, v128
	v_add_f32_e32 v19, v21, v129
	v_add_u32_e32 v20, 0xa400, v65
	ds_write2_b32 v20, v18, v19 offset0:8 offset1:140
	v_add_u32_e32 v35, 0xb000, v65
	v_add_f32_e32 v2, v2, v126
	v_add_f32_e32 v3, v3, v127
	s_waitcnt vmcnt(10)
	v_add_f32_e32 v22, v22, v130
	v_add_f32_e32 v23, v23, v131
	ds_write2_b32 v35, v22, v23 offset0:32 offset1:164
	v_add_f32_e32 v22, v24, v132
	v_add_f32_e32 v23, v25, v133
	v_add_u32_e32 v24, 0xb400, v65
	ds_write2_b32 v24, v22, v23 offset0:40 offset1:172
	v_add_u32_e32 v35, 0xc000, v65
	s_waitcnt vmcnt(9)
	v_add_f32_e32 v26, v26, v134
	v_add_f32_e32 v27, v27, v135
	ds_write2_b32 v35, v26, v27 offset0:64 offset1:196
	v_add_f32_e32 v26, v28, v136
	v_add_f32_e32 v27, v29, v137
	v_add_u32_e32 v28, 0xc400, v65
	ds_write2_b32 v28, v26, v27 offset0:72 offset1:204
	v_add_u32_e32 v35, 0xd000, v65
	s_waitcnt vmcnt(8)
	v_add_f32_e32 v30, v30, v138
	v_add_f32_e32 v31, v31, v139
	ds_write2_b32 v35, v30, v31 offset0:96 offset1:228
	v_add_f32_e32 v30, v32, v140
	v_add_f32_e32 v31, v33, v141
	v_add_u32_e32 v32, 0xd400, v65
	ds_write2_b32 v32, v30, v31 offset0:104 offset1:236
	v_add_u32_e32 v30, 0xa000, v66
	ds_write2_b32 v30, v2, v3 offset1:132
	v_add_f32_e32 v2, v4, v128
	v_add_f32_e32 v3, v5, v129
	v_add_u32_e32 v4, 0xa400, v66
	ds_write2_b32 v4, v2, v3 offset0:8 offset1:140
	v_add_f32_e32 v2, v6, v130
	v_add_f32_e32 v3, v7, v131
	v_add_u32_e32 v4, 0xb000, v66
	ds_write2_b32 v4, v2, v3 offset0:32 offset1:164
	v_add_f32_e32 v2, v8, v132
	v_add_f32_e32 v3, v9, v133
	v_add_u32_e32 v4, 0xb400, v66
	ds_write2_b32 v4, v2, v3 offset0:40 offset1:172
	v_add_f32_e32 v2, v10, v134
	v_add_f32_e32 v3, v11, v135
	v_add_u32_e32 v4, 0xc000, v66
	ds_write2_b32 v4, v2, v3 offset0:64 offset1:196
	v_add_f32_e32 v2, v12, v136
	v_add_f32_e32 v3, v13, v137
	v_add_u32_e32 v4, 0xc400, v66
	ds_write2_b32 v4, v2, v3 offset0:72 offset1:204
	v_add_f32_e32 v2, v14, v138
	v_add_f32_e32 v3, v15, v139
	v_add_u32_e32 v4, 0xd000, v66
	v_add_co_u32_e32 v6, vcc, s10, v58
	ds_write2_b32 v4, v2, v3 offset0:96 offset1:228
	v_add_f32_e32 v2, v16, v140
	v_add_f32_e32 v3, v17, v141
	v_add_u32_e32 v4, 0xd400, v66
	v_addc_co_u32_e32 v7, vcc, 0, v59, vcc
	ds_write2_b32 v4, v2, v3 offset0:104 offset1:236
	s_waitcnt lgkmcnt(0)
	s_barrier
	s_waitcnt vmcnt(6)
	v_mov_b64_e32 v[2:3], v[142:143]
	v_mov_b64_e32 v[4:5], v[144:145]
	v_add_u32_e32 v24, v37, v39
	v_mov_b64_e32 v[6:7], v[146:147]
	v_mov_b64_e32 v[8:9], v[148:149]
	ds_read_b128 v[10:13], v24 offset:40960
	ds_read_b128 v[14:17], v24 offset:40976
	s_mov_b32 s10, 0x5a92000
	v_lshlrev_b32_e32 v18, 16, v2
	v_and_b32_e32 v19, 0xffff0000, v2
	v_lshlrev_b32_e32 v20, 16, v6
	v_mul_f32_e32 v2, 0xbfb8aa3b, v20
	v_exp_f32_e32 v2, v2
	v_and_b32_e32 v21, 0xffff0000, v6
	s_waitcnt lgkmcnt(1)
	v_pk_mul_f32 v[10:11], v[10:11], v[18:19]
	v_lshlrev_b32_e32 v6, 16, v7
	v_add_f32_e32 v2, 1.0, v2
	v_rcp_f32_e32 v22, v2
	v_mul_f32_e32 v2, 0xbfb8aa3b, v21
	v_exp_f32_e32 v2, v2
	v_pk_mul_f32 v[10:11], v[10:11], v[20:21]
	v_and_b32_e32 v7, 0xffff0000, v7
	v_add_f32_e32 v2, 1.0, v2
	v_rcp_f32_e32 v23, v2
	s_nop 0
	v_pk_mul_f32 v[10:11], v[10:11], v[22:23]
	s_nop 0
	v_cvt_pk_bf16_f32 v2, v10, v11
	v_lshlrev_b32_e32 v10, 16, v3
	v_and_b32_e32 v11, 0xffff0000, v3
	v_mul_f32_e32 v3, 0xbfb8aa3b, v6
	v_exp_f32_e32 v3, v3
	v_pk_mul_f32 v[10:11], v[12:13], v[10:11]
	v_add_f32_e32 v3, 1.0, v3
	v_rcp_f32_e32 v18, v3
	v_mul_f32_e32 v3, 0xbfb8aa3b, v7
	v_exp_f32_e32 v3, v3
	v_pk_mul_f32 v[10:11], v[10:11], v[6:7]
	v_add_f32_e32 v3, 1.0, v3
	v_rcp_f32_e32 v19, v3
	s_nop 0
	v_pk_mul_f32 v[6:7], v[10:11], v[18:19]
	v_lshlrev_b32_e32 v10, 16, v8
	v_cvt_pk_bf16_f32 v3, v6, v7
	v_lshlrev_b32_e32 v6, 16, v4
	v_and_b32_e32 v7, 0xffff0000, v4
	v_mul_f32_e32 v4, 0xbfb8aa3b, v10
	v_exp_f32_e32 v4, v4
	v_and_b32_e32 v11, 0xffff0000, v8
	s_waitcnt lgkmcnt(0)
	v_pk_mul_f32 v[6:7], v[14:15], v[6:7]
	v_lshlrev_b32_e32 v8, 16, v9
	v_add_f32_e32 v4, 1.0, v4
	v_rcp_f32_e32 v12, v4
	v_mul_f32_e32 v4, 0xbfb8aa3b, v11
	v_exp_f32_e32 v4, v4
	v_pk_mul_f32 v[6:7], v[6:7], v[10:11]
	v_and_b32_e32 v9, 0xffff0000, v9
	v_add_co_u32_e32 v18, vcc, s10, v58
	v_add_f32_e32 v4, 1.0, v4
	v_rcp_f32_e32 v13, v4
	v_addc_co_u32_e32 v19, vcc, 0, v59, vcc
	s_mov_b32 s10, 0x5a93000
	v_pk_mul_f32 v[6:7], v[6:7], v[12:13]
	s_nop 0
	v_cvt_pk_bf16_f32 v4, v6, v7
	v_lshlrev_b32_e32 v6, 16, v5
	v_and_b32_e32 v7, 0xffff0000, v5
	v_mul_f32_e32 v5, 0xbfb8aa3b, v8
	v_exp_f32_e32 v5, v5
	v_pk_mul_f32 v[6:7], v[16:17], v[6:7]
	v_add_f32_e32 v5, 1.0, v5
	v_rcp_f32_e32 v10, v5
	v_mul_f32_e32 v5, 0xbfb8aa3b, v9
	v_exp_f32_e32 v5, v5
	v_pk_mul_f32 v[6:7], v[6:7], v[8:9]
	v_add_f32_e32 v5, 1.0, v5
	v_rcp_f32_e32 v11, v5
	s_nop 0
	v_pk_mul_f32 v[6:7], v[6:7], v[10:11]
	s_nop 0
	v_cvt_pk_bf16_f32 v5, v6, v7
	v_add_co_u32_e32 v6, vcc, s10, v58
	global_store_dwordx4 v[60:61], v[2:5], off
	s_nop 0
	v_addc_co_u32_e32 v7, vcc, 0, v59, vcc
	s_waitcnt vmcnt(5)
	v_mov_b64_e32 v[2:3], v[150:151]
	v_mov_b64_e32 v[4:5], v[152:153]
	s_nop 0
	v_mov_b64_e32 v[6:7], v[154:155]
	v_mov_b64_e32 v[8:9], v[156:157]
	ds_read_b128 v[10:13], v24 offset:57856
	ds_read_b128 v[14:17], v24 offset:57872
	s_mov_b32 s10, 0x5b22000
	v_lshlrev_b32_e32 v20, 16, v2
	v_lshlrev_b32_e32 v22, 16, v6
	v_and_b32_e32 v21, 0xffff0000, v2
	v_mul_f32_e32 v2, 0xbfb8aa3b, v22
	v_exp_f32_e32 v2, v2
	v_and_b32_e32 v23, 0xffff0000, v6
	s_waitcnt lgkmcnt(1)
; __device__ __forceinline__ unsigned cvt_pk_bf16(float lo, float hi) { f32x2 v = {lo, hi}; bf16x2_t b = __builtin_convertvector(v, bf16x2_t); return __builtin_bit_cast(unsigned, b); }
; __device__ __forceinline__ float bf_lo(unsigned w) { return __uint_as_float(w << 16); }
; __device__ __forceinline__ float bf_hi(unsigned w) { return __uint_as_float(w & 0xffff0000u); }
; __device__ __forceinline__ float sigmoidf_fast(float x) { return __builtin_amdgcn_rcpf(1.0f + __builtin_amdgcn_exp2f(-1.4426950408889634f * x)); }
; #define LAS __attribute__((address_space(3)))
; __device__ __forceinline__ void gate_unit(LAS unsigned char* lds, bf16_t* Zg, int ch, const bf16_t* wsb, const float* ln_g, const float* ln_b, const float* b_s, bool dostore = true) {
;     ...
;         for (int i = 0; i < 4; ++i) { const int p = (tid >> 4) + 32 * i, c8 = (tid & 15) * 8; bf16_t* zr = Zc + (size_t)p * ZLD + g * 128 + c8;
;             const u32x4 uw = *(const u32x4*)(zr + COL_U), gw = *(const u32x4*)(zr + COL_GB);
;             const f32x4 s0 = *(const LAS f32x4*)(st + p * 132 + c8), s1 = *(const LAS f32x4*)(st + p * 132 + c8 + 4);
;             const float sv[8] = {s0.x, s0.y, s0.z, s0.w, s1.x, s1.y, s1.z, s1.w}; u32x4 ow;
; #pragma unroll
;             for (int e = 0; e < 4; ++e) { const float u0 = bf_lo(uw[e]), u1 = bf_hi(uw[e]), g0 = bf_lo(gw[e]), g1 = bf_hi(gw[e]);
;                 ow[e] = cvt_pk_bf16(u0 * sv[2 * e] * g0 * sigmoidf_fast(g0), u1 * sv[2 * e + 1] * g1 * sigmoidf_fast(g1)); }
;             if (dostore) *(u32x4*)(zr + COL_U) = ow; }
	v_pk_mul_f32 v[10:11], v[10:11], v[20:21]
	v_lshlrev_b32_e32 v6, 16, v7
	v_add_f32_e32 v2, 1.0, v2
	v_rcp_f32_e32 v24, v2
	v_mul_f32_e32 v2, 0xbfb8aa3b, v23
	v_exp_f32_e32 v2, v2
	v_pk_mul_f32 v[10:11], v[10:11], v[22:23]
	v_and_b32_e32 v7, 0xffff0000, v7
	v_add_f32_e32 v2, 1.0, v2
	v_rcp_f32_e32 v25, v2
	s_nop 0
	v_pk_mul_f32 v[10:11], v[10:11], v[24:25]
	s_nop 0
	v_cvt_pk_bf16_f32 v2, v10, v11
	v_lshlrev_b32_e32 v10, 16, v3
	v_and_b32_e32 v11, 0xffff0000, v3
	v_mul_f32_e32 v3, 0xbfb8aa3b, v6
	v_exp_f32_e32 v3, v3
	v_pk_mul_f32 v[10:11], v[12:13], v[10:11]
	v_add_f32_e32 v3, 1.0, v3
	v_rcp_f32_e32 v20, v3
	v_mul_f32_e32 v3, 0xbfb8aa3b, v7
	v_exp_f32_e32 v3, v3
	v_pk_mul_f32 v[10:11], v[10:11], v[6:7]
	v_add_f32_e32 v3, 1.0, v3
	v_rcp_f32_e32 v21, v3
	s_nop 0
	v_pk_mul_f32 v[6:7], v[10:11], v[20:21]
	v_lshlrev_b32_e32 v10, 16, v8
	v_cvt_pk_bf16_f32 v3, v6, v7
	v_lshlrev_b32_e32 v6, 16, v4
	v_and_b32_e32 v7, 0xffff0000, v4
	v_mul_f32_e32 v4, 0xbfb8aa3b, v10
	v_exp_f32_e32 v4, v4
	v_and_b32_e32 v11, 0xffff0000, v8
	s_waitcnt lgkmcnt(0)
	v_pk_mul_f32 v[6:7], v[14:15], v[6:7]
	v_lshlrev_b32_e32 v8, 16, v9
	v_add_f32_e32 v4, 1.0, v4
	v_rcp_f32_e32 v12, v4
	v_mul_f32_e32 v4, 0xbfb8aa3b, v11
	v_exp_f32_e32 v4, v4
	v_pk_mul_f32 v[6:7], v[6:7], v[10:11]
	v_and_b32_e32 v9, 0xffff0000, v9
	v_add_f32_e32 v4, 1.0, v4
	v_rcp_f32_e32 v13, v4
	s_nop 0
	v_pk_mul_f32 v[6:7], v[6:7], v[12:13]
	s_nop 0
	v_cvt_pk_bf16_f32 v4, v6, v7
	v_lshlrev_b32_e32 v6, 16, v5
	v_and_b32_e32 v7, 0xffff0000, v5
	v_mul_f32_e32 v5, 0xbfb8aa3b, v8
	v_exp_f32_e32 v5, v5
	v_pk_mul_f32 v[6:7], v[16:17], v[6:7]
	v_add_f32_e32 v5, 1.0, v5
	v_rcp_f32_e32 v10, v5
	v_mul_f32_e32 v5, 0xbfb8aa3b, v9
	v_exp_f32_e32 v5, v5
	v_pk_mul_f32 v[6:7], v[6:7], v[8:9]
	v_add_f32_e32 v5, 1.0, v5
	v_rcp_f32_e32 v11, v5
	s_nop 0
	v_pk_mul_f32 v[6:7], v[6:7], v[10:11]
	s_nop 0
	v_cvt_pk_bf16_f32 v5, v6, v7
	global_store_dwordx4 v[18:19], v[2:5], off
	v_add_co_u32_e32 v18, vcc, s10, v58
	s_mov_b32 s10, 0x5b23000
	s_nop 0
	v_addc_co_u32_e32 v19, vcc, 0, v59, vcc
	v_add_co_u32_e32 v6, vcc, s10, v58
	s_mov_b32 s10, 0x5bb2000
	s_nop 0
	v_addc_co_u32_e32 v7, vcc, 0, v59, vcc
	s_waitcnt vmcnt(4)
	v_mov_b64_e32 v[2:3], v[158:159]
	v_mov_b64_e32 v[4:5], v[160:161]
	s_nop 0
	v_mov_b64_e32 v[6:7], v[162:163]
	v_mov_b64_e32 v[8:9], v[164:165]
	ds_read_b128 v[10:13], v67 offset:40960
	ds_read_b128 v[14:17], v67 offset:40976
	v_lshlrev_b32_e32 v20, 16, v2
	v_lshlrev_b32_e32 v22, 16, v6
	v_and_b32_e32 v21, 0xffff0000, v2
	v_mul_f32_e32 v2, 0xbfb8aa3b, v22
	v_exp_f32_e32 v2, v2
	v_and_b32_e32 v23, 0xffff0000, v6
	s_waitcnt lgkmcnt(1)
	v_pk_mul_f32 v[10:11], v[10:11], v[20:21]
	v_lshlrev_b32_e32 v6, 16, v7
	v_add_f32_e32 v2, 1.0, v2
	v_rcp_f32_e32 v24, v2
	v_mul_f32_e32 v2, 0xbfb8aa3b, v23
	v_exp_f32_e32 v2, v2
	v_pk_mul_f32 v[10:11], v[10:11], v[22:23]
	v_and_b32_e32 v7, 0xffff0000, v7
	v_add_f32_e32 v2, 1.0, v2
	v_rcp_f32_e32 v25, v2
	s_nop 0
	v_pk_mul_f32 v[10:11], v[10:11], v[24:25]
	s_nop 0
	v_cvt_pk_bf16_f32 v2, v10, v11
	v_lshlrev_b32_e32 v10, 16, v3
	v_and_b32_e32 v11, 0xffff0000, v3
	v_mul_f32_e32 v3, 0xbfb8aa3b, v6
	v_exp_f32_e32 v3, v3
	v_pk_mul_f32 v[10:11], v[12:13], v[10:11]
	v_add_f32_e32 v3, 1.0, v3
	v_rcp_f32_e32 v20, v3
	v_mul_f32_e32 v3, 0xbfb8aa3b, v7
	v_exp_f32_e32 v3, v3
	v_pk_mul_f32 v[10:11], v[10:11], v[6:7]
	v_add_f32_e32 v3, 1.0, v3
	v_rcp_f32_e32 v21, v3
	s_nop 0
	v_pk_mul_f32 v[6:7], v[10:11], v[20:21]
	v_lshlrev_b32_e32 v10, 16, v8
	v_cvt_pk_bf16_f32 v3, v6, v7
	v_lshlrev_b32_e32 v6, 16, v4
	v_and_b32_e32 v7, 0xffff0000, v4
	v_mul_f32_e32 v4, 0xbfb8aa3b, v10
	v_exp_f32_e32 v4, v4
	v_and_b32_e32 v11, 0xffff0000, v8
	s_waitcnt lgkmcnt(0)
; __device__ __forceinline__ unsigned cvt_pk_bf16(float lo, float hi) { f32x2 v = {lo, hi}; bf16x2_t b = __builtin_convertvector(v, bf16x2_t); return __builtin_bit_cast(unsigned, b); }
; __device__ __forceinline__ float bf_lo(unsigned w) { return __uint_as_float(w << 16); }
; __device__ __forceinline__ float bf_hi(unsigned w) { return __uint_as_float(w & 0xffff0000u); }
; __device__ __forceinline__ float sigmoidf_fast(float x) { return __builtin_amdgcn_rcpf(1.0f + __builtin_amdgcn_exp2f(-1.4426950408889634f * x)); }
; #define LAS __attribute__((address_space(3)))
; __device__ __forceinline__ void gate_unit(LAS unsigned char* lds, bf16_t* Zg, int ch, const bf16_t* wsb, const float* ln_g, const float* ln_b, const float* b_s, bool dostore = true) {
;     ...
;         for (int i = 0; i < 4; ++i) { const int p = (tid >> 4) + 32 * i, c8 = (tid & 15) * 8; bf16_t* zr = Zc + (size_t)p * ZLD + g * 128 + c8;
;             const u32x4 uw = *(const u32x4*)(zr + COL_U), gw = *(const u32x4*)(zr + COL_GB);
;             const f32x4 s0 = *(const LAS f32x4*)(st + p * 132 + c8), s1 = *(const LAS f32x4*)(st + p * 132 + c8 + 4);
;             const float sv[8] = {s0.x, s0.y, s0.z, s0.w, s1.x, s1.y, s1.z, s1.w}; u32x4 ow;
; #pragma unroll
;             for (int e = 0; e < 4; ++e) { const float u0 = bf_lo(uw[e]), u1 = bf_hi(uw[e]), g0 = bf_lo(gw[e]), g1 = bf_hi(gw[e]);
;                 ow[e] = cvt_pk_bf16(u0 * sv[2 * e] * g0 * sigmoidf_fast(g0), u1 * sv[2 * e + 1] * g1 * sigmoidf_fast(g1)); }
;             if (dostore) *(u32x4*)(zr + COL_U) = ow; }
;         __syncthreads();
;     }
	v_pk_mul_f32 v[6:7], v[14:15], v[6:7]
	v_lshlrev_b32_e32 v8, 16, v9
	v_add_f32_e32 v4, 1.0, v4
	v_rcp_f32_e32 v12, v4
	v_mul_f32_e32 v4, 0xbfb8aa3b, v11
	v_exp_f32_e32 v4, v4
	v_pk_mul_f32 v[6:7], v[6:7], v[10:11]
	v_and_b32_e32 v9, 0xffff0000, v9
	v_add_f32_e32 v4, 1.0, v4
	v_rcp_f32_e32 v13, v4
	s_nop 0
	v_pk_mul_f32 v[6:7], v[6:7], v[12:13]
	s_nop 0
	v_cvt_pk_bf16_f32 v4, v6, v7
	v_lshlrev_b32_e32 v6, 16, v5
	v_and_b32_e32 v7, 0xffff0000, v5
	v_mul_f32_e32 v5, 0xbfb8aa3b, v8
	v_exp_f32_e32 v5, v5
	v_pk_mul_f32 v[6:7], v[16:17], v[6:7]
	v_add_f32_e32 v5, 1.0, v5
	v_rcp_f32_e32 v10, v5
	v_mul_f32_e32 v5, 0xbfb8aa3b, v9
	v_exp_f32_e32 v5, v5
	v_pk_mul_f32 v[6:7], v[6:7], v[8:9]
	v_add_f32_e32 v5, 1.0, v5
	v_rcp_f32_e32 v11, v5
	s_nop 0
	v_pk_mul_f32 v[6:7], v[6:7], v[10:11]
	s_nop 0
	v_cvt_pk_bf16_f32 v5, v6, v7
	global_store_dwordx4 v[18:19], v[2:5], off
	v_add_co_u32_e32 v18, vcc, s10, v58
	s_mov_b32 s10, 0x5bb3000
	s_nop 0
	v_addc_co_u32_e32 v19, vcc, 0, v59, vcc
	v_add_co_u32_e32 v6, vcc, s10, v58
	s_nop 1
	v_addc_co_u32_e32 v7, vcc, 0, v59, vcc
	s_waitcnt vmcnt(3)
	v_mov_b64_e32 v[2:3], v[166:167]
	v_mov_b64_e32 v[4:5], v[168:169]
	s_nop 0
	v_mov_b64_e32 v[6:7], v[170:171]
	v_mov_b64_e32 v[8:9], v[172:173]
	ds_read_b128 v[10:13], v67 offset:57856
	ds_read_b128 v[14:17], v67 offset:57872
	v_lshlrev_b32_e32 v20, 16, v2
	v_lshlrev_b32_e32 v22, 16, v6
	v_and_b32_e32 v21, 0xffff0000, v2
	v_mul_f32_e32 v2, 0xbfb8aa3b, v22
	v_exp_f32_e32 v2, v2
	v_and_b32_e32 v23, 0xffff0000, v6
	s_waitcnt lgkmcnt(1)
	v_pk_mul_f32 v[10:11], v[10:11], v[20:21]
	v_lshlrev_b32_e32 v6, 16, v7
	v_add_f32_e32 v2, 1.0, v2
	v_rcp_f32_e32 v24, v2
	v_mul_f32_e32 v2, 0xbfb8aa3b, v23
	v_exp_f32_e32 v2, v2
	v_pk_mul_f32 v[10:11], v[10:11], v[22:23]
	v_and_b32_e32 v7, 0xffff0000, v7
	v_add_f32_e32 v2, 1.0, v2
	v_rcp_f32_e32 v25, v2
	s_nop 0
	v_pk_mul_f32 v[10:11], v[10:11], v[24:25]
	s_nop 0
	v_cvt_pk_bf16_f32 v2, v10, v11
	v_lshlrev_b32_e32 v10, 16, v3
	v_and_b32_e32 v11, 0xffff0000, v3
	v_mul_f32_e32 v3, 0xbfb8aa3b, v6
	v_exp_f32_e32 v3, v3
	v_pk_mul_f32 v[10:11], v[12:13], v[10:11]
	v_add_f32_e32 v3, 1.0, v3
	v_rcp_f32_e32 v20, v3
	v_mul_f32_e32 v3, 0xbfb8aa3b, v7
	v_exp_f32_e32 v3, v3
	v_pk_mul_f32 v[10:11], v[10:11], v[6:7]
	v_add_f32_e32 v3, 1.0, v3
	v_rcp_f32_e32 v21, v3
	s_nop 0
	v_pk_mul_f32 v[6:7], v[10:11], v[20:21]
	v_lshlrev_b32_e32 v10, 16, v8
	v_cvt_pk_bf16_f32 v3, v6, v7
	v_lshlrev_b32_e32 v6, 16, v4
	v_and_b32_e32 v7, 0xffff0000, v4
	v_mul_f32_e32 v4, 0xbfb8aa3b, v10
	v_exp_f32_e32 v4, v4
	v_and_b32_e32 v11, 0xffff0000, v8
	s_waitcnt lgkmcnt(0)
	v_pk_mul_f32 v[6:7], v[14:15], v[6:7]
	v_lshlrev_b32_e32 v8, 16, v9
	v_add_f32_e32 v4, 1.0, v4
	v_rcp_f32_e32 v12, v4
	v_mul_f32_e32 v4, 0xbfb8aa3b, v11
	v_exp_f32_e32 v4, v4
	v_pk_mul_f32 v[6:7], v[6:7], v[10:11]
	v_and_b32_e32 v9, 0xffff0000, v9
	v_add_f32_e32 v4, 1.0, v4
	v_rcp_f32_e32 v13, v4
	s_nop 0
	v_pk_mul_f32 v[6:7], v[6:7], v[12:13]
	s_nop 0
	v_cvt_pk_bf16_f32 v4, v6, v7
	v_lshlrev_b32_e32 v6, 16, v5
	v_and_b32_e32 v7, 0xffff0000, v5
	v_mul_f32_e32 v5, 0xbfb8aa3b, v8
	v_exp_f32_e32 v5, v5
	v_pk_mul_f32 v[6:7], v[16:17], v[6:7]
	v_add_f32_e32 v5, 1.0, v5
	v_rcp_f32_e32 v10, v5
	v_mul_f32_e32 v5, 0xbfb8aa3b, v9
	v_exp_f32_e32 v5, v5
	v_pk_mul_f32 v[6:7], v[6:7], v[8:9]
	v_add_f32_e32 v5, 1.0, v5
	v_rcp_f32_e32 v11, v5
	s_nop 0
	v_pk_mul_f32 v[6:7], v[6:7], v[10:11]
	s_nop 0
	v_cvt_pk_bf16_f32 v5, v6, v7
	global_store_dwordx4 v[18:19], v[2:5], off
	s_barrier
	s_cbranch_scc1 .LBB0_183
	s_add_i32 s15, s15, s3
	s_add_u32 s12, s12, s24
	s_addc_u32 s13, s13, s18
	s_add_u32 s8, s8, s24
	s_addc_u32 s9, s9, s18
	s_add_u32 s6, s6, s24
	s_addc_u32 s7, s7, s18
	s_cmpk_gt_i32 s15, 0xff
	s_cbranch_scc0 .LBB0_178
